# v50 + MLP1 x2 and WIN: peeled first K iteration lets the previous tile's 16 result stores stay in flight through its first two DMA waits (vmcnt 24), strict waits kept for the first tile via a flag
# speedup vs baseline: 1.0051x; 1.0051x over previous
.LBB0_739:
	s_lshl_b32 s10, s10, 5
	s_lshl_b32 s30, s11, 6
	s_lshl_b32 s14, s11, 13
	s_and_b32 s31, s10, 0x60
	s_mov_b64 s[10:11], 0x80
	s_add_i32 m0, s19, 0x18000
	v_lshl_add_u64 v[8:9], v[8:9], 0, s[10:11]
	s_lshl_b32 s15, s31, 7
	s_waitcnt vmcnt(2)
	s_barrier
	global_load_lds_dwordx4 v[8:9], off
	v_lshl_add_u64 v[6:7], v[6:7], 0, s[10:11]
	s_add_i32 m0, s19, 0x1a000
	s_add_i32 s33, s19, 0x8000
	s_add_i32 s35, s19, 0xa000
	global_load_lds_dwordx4 v[6:7], off
	v_lshl_add_u64 v[2:3], v[2:3], 0, s[10:11]
	s_mov_b32 m0, s33
	s_add_u32 s12, s44, 0x40080
	global_load_lds_dwordx4 v[2:3], off
	v_lshl_add_u64 v[2:3], v[4:5], 0, s[10:11]
	s_mov_b32 m0, s35
	s_addc_u32 s13, s45, 0
	global_load_lds_dwordx4 v[2:3], off
	s_add_i32 m0, s19, 0x1c000
	v_lshl_add_u64 v[2:3], s[12:13], 0, v[134:135]
	global_load_lds_dwordx4 v[2:3], off
	v_lshl_add_u64 v[2:3], s[12:13], 0, v[130:131]
	s_add_i32 m0, s19, 0x1e000
	v_bfe_u32 v148, v0, 4, 2
	global_load_lds_dwordx4 v[2:3], off
	s_sext_i32_i8 s64, s4
	v_and_b32_e32 v1, 15, v0
	v_lshlrev_b32_e32 v2, 4, v148
	v_lshlrev_b32_e32 v4, 2, v0
	v_lshlrev_b32_e32 v5, 6, v0
	s_movk_i32 s4, 0x3c0
	v_lshl_or_b32 v3, v1, 6, v2
	v_and_b32_e32 v4, 32, v4
	v_and_or_b32 v2, v5, s4, v2
	v_bitop3_b32 v149, s15, v2, v4 bitop3:0xf6
	v_lshlrev_b32_e32 v2, 8, v0
	v_bitop3_b32 v3, v3, s14, v4 bitop3:0xde
	s_waitcnt vmcnt(6)
	s_cmpk_lt_u32 s5, 0x100
	v_and_b32_e32 v2, 0x18000, v2
	v_lshlrev_b32_e32 v4, 11, v12
	s_cselect_b64 s[12:13], -1, 0
	v_readlane_b32 s4, v249, 2
	v_or3_b32 v2, v10, v2, v4
	s_add_i32 s49, 0, 0x10000
	s_add_i32 s62, 0, 0x14000
	s_ashr_i32 s48, s4, 31
	v_add_u32_e32 v138, v2, v11
	v_mov_b32_e32 v139, v135
	v_add3_u32 v140, v13, v10, v11
	v_mov_b32_e32 v141, v135
	v_mov_b64_e32 v[142:143], 0x500
	v_mov_b64_e32 v[144:145], 0x4ff
	v_add_u32_e32 v150, s49, v149
	v_add_u32_e32 v151, s62, v149
	v_add_u32_e32 v152, 0, v3
	s_barrier
	v_readlane_b32 s5, v249, 3
	s_waitcnt vmcnt(0)
	s_mov_b32 s100, 1
	s_branch .LBB0_742

.LBB0_744:
	s_add_u32 s36, s96, s22
	s_addc_u32 s37, s97, s23
	s_and_b64 s[14:15], s[4:5], exec
	s_cselect_b32 s14, s37, s43
	s_cselect_b32 s15, s36, s42
	s_add_u32 s38, s2, s26
	s_addc_u32 s39, s3, s27
	s_and_b64 s[46:47], s[4:5], exec
	s_cselect_b32 s21, s39, s45
	s_cselect_b32 s65, s38, s44
	s_add_u32 s42, s42, 0x40080
	s_addc_u32 s43, s43, 0
	s_add_u32 s66, s44, 0x100
	s_addc_u32 s67, s45, 0
	s_mov_b32 s68, -2
	ds_read_b128 v[154:157], v150
	ds_read_b128 v[158:161], v150 offset:1024
	ds_read_b128 v[162:165], v150 offset:2048
	ds_read_b128 v[166:169], v150 offset:3072
	ds_read_b128 v[170:173], v151
	ds_read_b128 v[174:177], v151 offset:1024
	ds_read_b128 v[178:181], v151 offset:2048
	ds_read_b128 v[182:185], v151 offset:3072
	s_add_u32 s44, s42, 0xfffc0080
	s_addc_u32 s45, s43, -1
	s_cmp_eq_u32 s68, 12
	s_cselect_b32 s47, s14, s45
	s_cselect_b32 s46, s15, s44
	s_cselect_b32 s45, s21, s67
	s_cselect_b32 s44, s65, s66
	v_lshl_add_u64 v[146:147], s[42:43], 0, v[138:139]
	s_add_i32 m0, s19, 0xc000
	ds_read_b128 v[186:189], v152
	ds_read_b128 v[190:193], v152 offset:1024
	ds_read_b128 v[194:197], v152 offset:2048
	ds_read_b128 v[198:201], v152 offset:3072
	ds_read_b128 v[206:209], v152 offset:4096
	ds_read_b128 v[210:213], v152 offset:5120
	ds_read_b128 v[214:217], v152 offset:6144
	ds_read_b128 v[218:221], v152 offset:7168
	global_load_lds_dwordx4 v[146:147], off
	v_lshl_add_u64 v[146:147], s[42:43], 0, v[140:141]
	s_add_i32 m0, s19, 0xe000
	s_nop 0
	global_load_lds_dwordx4 v[146:147], off
	s_waitcnt vmcnt(24)
	s_cmp_eq_u32 s100, 0
	s_cbranch_scc1 .Lrd_742_a
	s_waitcnt vmcnt(8)
.Lrd_742_a:
	s_waitcnt lgkmcnt(0)
	s_barrier
	s_setprio 1
	s_waitcnt lgkmcnt(0)
	v_mfma_f32_16x16x32_bf16 v[126:129], v[154:157], v[186:189], 0
	v_mfma_f32_16x16x32_bf16 v[122:125], v[162:165], v[186:189], 0
	v_mfma_f32_16x16x32_bf16 v[110:113], v[154:157], v[194:197], 0
	v_mfma_f32_16x16x32_bf16 v[106:109], v[162:165], v[194:197], 0
	v_mfma_f32_16x16x32_bf16 v[94:97], v[154:157], v[206:209], 0
	v_mfma_f32_16x16x32_bf16 v[90:93], v[162:165], v[206:209], 0
	v_mfma_f32_16x16x32_bf16 v[78:81], v[154:157], v[214:217], 0
	v_mfma_f32_16x16x32_bf16 v[74:77], v[162:165], v[214:217], 0
	v_mfma_f32_16x16x32_bf16 v[126:129], v[158:161], v[190:193], v[126:129]
	v_mfma_f32_16x16x32_bf16 v[122:125], v[166:169], v[190:193], v[122:125]
	v_mfma_f32_16x16x32_bf16 v[110:113], v[158:161], v[198:201], v[110:113]
	v_mfma_f32_16x16x32_bf16 v[106:109], v[166:169], v[198:201], v[106:109]
	v_mfma_f32_16x16x32_bf16 v[94:97], v[158:161], v[210:213], v[94:97]
	v_mfma_f32_16x16x32_bf16 v[90:93], v[166:169], v[210:213], v[90:93]
	v_mfma_f32_16x16x32_bf16 v[78:81], v[158:161], v[218:221], v[78:81]
	v_mfma_f32_16x16x32_bf16 v[74:77], v[166:169], v[218:221], v[74:77]
	s_setprio 0
	s_setprio 1
	v_mfma_f32_16x16x32_bf16 v[118:121], v[170:173], v[186:189], 0
	v_mfma_f32_16x16x32_bf16 v[114:117], v[178:181], v[186:189], 0
	v_mfma_f32_16x16x32_bf16 v[102:105], v[170:173], v[194:197], 0
	v_mfma_f32_16x16x32_bf16 v[98:101], v[178:181], v[194:197], 0
	v_mfma_f32_16x16x32_bf16 v[86:89], v[170:173], v[206:209], 0
	v_mfma_f32_16x16x32_bf16 v[82:85], v[178:181], v[206:209], 0
	v_mfma_f32_16x16x32_bf16 v[70:73], v[170:173], v[214:217], 0
	v_mfma_f32_16x16x32_bf16 v[66:69], v[178:181], v[214:217], 0
	v_mfma_f32_16x16x32_bf16 v[118:121], v[174:177], v[190:193], v[118:121]
	v_mfma_f32_16x16x32_bf16 v[114:117], v[182:185], v[190:193], v[114:117]
	v_mfma_f32_16x16x32_bf16 v[102:105], v[174:177], v[198:201], v[102:105]
	v_mfma_f32_16x16x32_bf16 v[98:101], v[182:185], v[198:201], v[98:101]
	v_mfma_f32_16x16x32_bf16 v[86:89], v[174:177], v[210:213], v[86:89]
	v_mfma_f32_16x16x32_bf16 v[82:85], v[182:185], v[210:213], v[82:85]
	v_mfma_f32_16x16x32_bf16 v[70:73], v[174:177], v[218:221], v[70:73]
	v_mfma_f32_16x16x32_bf16 v[66:69], v[182:185], v[218:221], v[66:69]
	s_setprio 0
	s_barrier
	s_add_i32 s69, s49, s16
	v_lshl_add_u64 v[146:147], s[44:45], 0, v[134:135]
	s_mov_b32 m0, s69
	ds_read_b128 v[186:189], v152 offset:16384
	ds_read_b128 v[190:193], v152 offset:17408
	ds_read_b128 v[194:197], v152 offset:18432
	ds_read_b128 v[198:201], v152 offset:19456
	ds_read_b128 v[206:209], v152 offset:20480
	ds_read_b128 v[210:213], v152 offset:21504
	ds_read_b128 v[214:217], v152 offset:22528
	ds_read_b128 v[218:221], v152 offset:23552
	global_load_lds_dwordx4 v[146:147], off
	s_add_i32 m0, s69, 0x2000
	s_add_u32 s70, s44, 0x40000
	v_lshl_add_u64 v[202:203], s[44:45], 0, v[130:131]
	s_addc_u32 s71, s45, 0
	s_add_i32 s69, s62, s16
	global_load_lds_dwordx4 v[202:203], off
	v_lshl_add_u64 v[222:223], s[70:71], 0, v[134:135]
	s_mov_b32 m0, s69
	v_lshl_add_u64 v[224:225], s[46:47], 0, v[132:133]
	global_load_lds_dwordx4 v[222:223], off
	v_lshl_add_u64 v[222:223], s[70:71], 0, v[130:131]
	s_add_i32 m0, s69, 0x2000
	s_nop 0
	global_load_lds_dwordx4 v[222:223], off
	v_lshl_add_u64 v[222:223], s[46:47], 0, v[136:137]
	s_mov_b32 m0, s19
	s_nop 0
	global_load_lds_dwordx4 v[222:223], off
	s_mov_b32 m0, s24
	s_nop 0
	global_load_lds_dwordx4 v[224:225], off
	s_waitcnt vmcnt(24)
	s_cmp_eq_u32 s100, 0
	s_cbranch_scc1 .Lrd_742_b
	s_waitcnt vmcnt(8)
.Lrd_742_b:
	s_mov_b32 s100, 0
	s_waitcnt lgkmcnt(0)
	s_barrier
	s_setprio 1
	s_waitcnt lgkmcnt(0)
	v_mfma_f32_16x16x32_bf16 v[62:65], v[154:157], v[186:189], 0
	v_mfma_f32_16x16x32_bf16 v[58:61], v[162:165], v[186:189], 0
	v_mfma_f32_16x16x32_bf16 v[46:49], v[154:157], v[194:197], 0
	v_mfma_f32_16x16x32_bf16 v[42:45], v[162:165], v[194:197], 0
	v_mfma_f32_16x16x32_bf16 v[30:33], v[154:157], v[206:209], 0
	v_mfma_f32_16x16x32_bf16 v[26:29], v[162:165], v[206:209], 0
	v_mfma_f32_16x16x32_bf16 v[14:17], v[154:157], v[214:217], 0
	v_mfma_f32_16x16x32_bf16 v[10:13], v[162:165], v[214:217], 0
	v_mfma_f32_16x16x32_bf16 v[62:65], v[158:161], v[190:193], v[62:65]
	v_mfma_f32_16x16x32_bf16 v[58:61], v[166:169], v[190:193], v[58:61]
	v_mfma_f32_16x16x32_bf16 v[46:49], v[158:161], v[198:201], v[46:49]
	v_mfma_f32_16x16x32_bf16 v[42:45], v[166:169], v[198:201], v[42:45]
	v_mfma_f32_16x16x32_bf16 v[30:33], v[158:161], v[210:213], v[30:33]
	v_mfma_f32_16x16x32_bf16 v[26:29], v[166:169], v[210:213], v[26:29]
	v_mfma_f32_16x16x32_bf16 v[14:17], v[158:161], v[218:221], v[14:17]
	v_mfma_f32_16x16x32_bf16 v[10:13], v[166:169], v[218:221], v[10:13]
	s_setprio 0
	s_setprio 1
	v_mfma_f32_16x16x32_bf16 v[54:57], v[170:173], v[186:189], 0
	v_mfma_f32_16x16x32_bf16 v[50:53], v[178:181], v[186:189], 0
	v_mfma_f32_16x16x32_bf16 v[38:41], v[170:173], v[194:197], 0
	v_mfma_f32_16x16x32_bf16 v[34:37], v[178:181], v[194:197], 0
	v_mfma_f32_16x16x32_bf16 v[22:25], v[170:173], v[206:209], 0
	v_mfma_f32_16x16x32_bf16 v[18:21], v[178:181], v[206:209], 0
	v_mfma_f32_16x16x32_bf16 v[6:9], v[170:173], v[214:217], 0
	v_mfma_f32_16x16x32_bf16 v[2:5], v[178:181], v[214:217], 0
	v_mfma_f32_16x16x32_bf16 v[54:57], v[174:177], v[190:193], v[54:57]
	v_mfma_f32_16x16x32_bf16 v[50:53], v[182:185], v[190:193], v[50:53]
	v_mfma_f32_16x16x32_bf16 v[38:41], v[174:177], v[198:201], v[38:41]
	v_mfma_f32_16x16x32_bf16 v[34:37], v[182:185], v[198:201], v[34:37]
	v_mfma_f32_16x16x32_bf16 v[22:25], v[174:177], v[210:213], v[22:25]
	v_mfma_f32_16x16x32_bf16 v[18:21], v[182:185], v[210:213], v[18:21]
	v_mfma_f32_16x16x32_bf16 v[6:9], v[174:177], v[218:221], v[6:9]
	v_mfma_f32_16x16x32_bf16 v[2:5], v[182:185], v[218:221], v[2:5]
	s_setprio 0
	s_barrier
	s_add_i32 s69, 0, 0x18000
	v_add_u32_e32 v153, s69, v149
	s_add_i32 s70, 0, 0x1c000
	ds_read_b128 v[154:157], v153
	ds_read_b128 v[158:161], v153 offset:1024
	ds_read_b128 v[162:165], v153 offset:2048
	ds_read_b128 v[166:169], v153 offset:3072
	v_add_u32_e32 v153, s70, v149
	ds_read_b128 v[170:173], v153
	ds_read_b128 v[174:177], v153 offset:1024
	ds_read_b128 v[178:181], v153 offset:2048
	ds_read_b128 v[182:185], v153 offset:3072
	s_add_u32 s46, s46, 0x40000
	s_addc_u32 s47, s47, 0
	s_mov_b32 m0, s25
	v_lshl_add_u64 v[226:227], s[46:47], 0, v[136:137]
	ds_read_b128 v[186:189], v152 offset:32768
	ds_read_b128 v[190:193], v152 offset:33792
	ds_read_b128 v[194:197], v152 offset:34816
	ds_read_b128 v[198:201], v152 offset:35840
	ds_read_b128 v[206:209], v152 offset:36864
	ds_read_b128 v[210:213], v152 offset:37888
	ds_read_b128 v[214:217], v152 offset:38912
	ds_read_b128 v[218:221], v152 offset:39936
	global_load_lds_dwordx4 v[226:227], off
	v_lshl_add_u64 v[226:227], s[46:47], 0, v[132:133]
	s_mov_b32 m0, s28
	s_nop 0
	global_load_lds_dwordx4 v[226:227], off
	s_waitcnt vmcnt(8)
	s_waitcnt lgkmcnt(0)
	s_barrier
	s_setprio 1
	s_waitcnt lgkmcnt(0)
	v_mfma_f32_16x16x32_bf16 v[126:129], v[154:157], v[186:189], v[126:129]
	v_mfma_f32_16x16x32_bf16 v[122:125], v[162:165], v[186:189], v[122:125]
	v_mfma_f32_16x16x32_bf16 v[110:113], v[154:157], v[194:197], v[110:113]
	v_mfma_f32_16x16x32_bf16 v[106:109], v[162:165], v[194:197], v[106:109]
	v_mfma_f32_16x16x32_bf16 v[94:97], v[154:157], v[206:209], v[94:97]
	v_mfma_f32_16x16x32_bf16 v[90:93], v[162:165], v[206:209], v[90:93]
	v_mfma_f32_16x16x32_bf16 v[78:81], v[154:157], v[214:217], v[78:81]
	v_mfma_f32_16x16x32_bf16 v[74:77], v[162:165], v[214:217], v[74:77]
	v_mfma_f32_16x16x32_bf16 v[126:129], v[158:161], v[190:193], v[126:129]
	v_mfma_f32_16x16x32_bf16 v[122:125], v[166:169], v[190:193], v[122:125]
	v_mfma_f32_16x16x32_bf16 v[110:113], v[158:161], v[198:201], v[110:113]
	v_mfma_f32_16x16x32_bf16 v[106:109], v[166:169], v[198:201], v[106:109]
	v_mfma_f32_16x16x32_bf16 v[94:97], v[158:161], v[210:213], v[94:97]
	v_mfma_f32_16x16x32_bf16 v[90:93], v[166:169], v[210:213], v[90:93]
	v_mfma_f32_16x16x32_bf16 v[78:81], v[158:161], v[218:221], v[78:81]
	v_mfma_f32_16x16x32_bf16 v[74:77], v[166:169], v[218:221], v[74:77]
	s_setprio 0
	s_setprio 1
	v_mfma_f32_16x16x32_bf16 v[118:121], v[170:173], v[186:189], v[118:121]
	v_mfma_f32_16x16x32_bf16 v[114:117], v[178:181], v[186:189], v[114:117]
	v_mfma_f32_16x16x32_bf16 v[102:105], v[170:173], v[194:197], v[102:105]
	v_mfma_f32_16x16x32_bf16 v[98:101], v[178:181], v[194:197], v[98:101]
	v_mfma_f32_16x16x32_bf16 v[86:89], v[170:173], v[206:209], v[86:89]
	v_mfma_f32_16x16x32_bf16 v[82:85], v[178:181], v[206:209], v[82:85]
	v_mfma_f32_16x16x32_bf16 v[70:73], v[170:173], v[214:217], v[70:73]
	v_mfma_f32_16x16x32_bf16 v[66:69], v[178:181], v[214:217], v[66:69]
	v_mfma_f32_16x16x32_bf16 v[118:121], v[174:177], v[190:193], v[118:121]
	v_mfma_f32_16x16x32_bf16 v[114:117], v[182:185], v[190:193], v[114:117]
	v_mfma_f32_16x16x32_bf16 v[102:105], v[174:177], v[198:201], v[102:105]
	v_mfma_f32_16x16x32_bf16 v[98:101], v[182:185], v[198:201], v[98:101]
	v_mfma_f32_16x16x32_bf16 v[86:89], v[174:177], v[210:213], v[86:89]
	v_mfma_f32_16x16x32_bf16 v[82:85], v[182:185], v[210:213], v[82:85]
	v_mfma_f32_16x16x32_bf16 v[70:73], v[174:177], v[218:221], v[70:73]
	v_mfma_f32_16x16x32_bf16 v[66:69], v[182:185], v[218:221], v[66:69]
	s_setprio 0
	s_barrier
	s_add_i32 s46, s69, s16
	v_lshl_add_u64 v[146:147], v[146:147], 0, s[10:11]
	s_mov_b32 m0, s46
	ds_read_b128 v[186:189], v152 offset:49152
	ds_read_b128 v[190:193], v152 offset:50176
	ds_read_b128 v[194:197], v152 offset:51200
	ds_read_b128 v[198:201], v152 offset:52224
	ds_read_b128 v[206:209], v152 offset:53248
	ds_read_b128 v[210:213], v152 offset:54272
	ds_read_b128 v[214:217], v152 offset:55296
	ds_read_b128 v[218:221], v152 offset:56320
	global_load_lds_dwordx4 v[146:147], off
	s_add_i32 m0, s46, 0x2000
	s_add_u32 s44, s44, 0x40080
	v_lshl_add_u64 v[146:147], v[202:203], 0, s[10:11]
	s_addc_u32 s45, s45, 0
	s_add_i32 s46, s70, s16
	global_load_lds_dwordx4 v[146:147], off
	v_lshl_add_u64 v[146:147], s[44:45], 0, v[134:135]
	s_mov_b32 m0, s46
	s_nop 0
	global_load_lds_dwordx4 v[146:147], off
	v_lshl_add_u64 v[146:147], s[44:45], 0, v[130:131]
	s_add_i32 m0, s46, 0x2000
	s_nop 0
	global_load_lds_dwordx4 v[146:147], off
	v_lshl_add_u64 v[146:147], v[222:223], 0, s[10:11]
	s_mov_b32 m0, s33
	s_nop 0
	global_load_lds_dwordx4 v[146:147], off
	v_lshl_add_u64 v[146:147], v[224:225], 0, s[10:11]
	s_mov_b32 m0, s35
	s_nop 0
	global_load_lds_dwordx4 v[146:147], off
	s_waitcnt vmcnt(8)
	s_waitcnt lgkmcnt(0)
	s_barrier
	s_setprio 1
	s_waitcnt lgkmcnt(0)
	v_mfma_f32_16x16x32_bf16 v[62:65], v[154:157], v[186:189], v[62:65]
	v_mfma_f32_16x16x32_bf16 v[58:61], v[162:165], v[186:189], v[58:61]
	v_mfma_f32_16x16x32_bf16 v[46:49], v[154:157], v[194:197], v[46:49]
	v_mfma_f32_16x16x32_bf16 v[42:45], v[162:165], v[194:197], v[42:45]
	v_mfma_f32_16x16x32_bf16 v[30:33], v[154:157], v[206:209], v[30:33]
	v_mfma_f32_16x16x32_bf16 v[26:29], v[162:165], v[206:209], v[26:29]
	v_mfma_f32_16x16x32_bf16 v[14:17], v[154:157], v[214:217], v[14:17]
	v_mfma_f32_16x16x32_bf16 v[10:13], v[162:165], v[214:217], v[10:13]
	v_mfma_f32_16x16x32_bf16 v[62:65], v[158:161], v[190:193], v[62:65]
	v_mfma_f32_16x16x32_bf16 v[58:61], v[166:169], v[190:193], v[58:61]
	v_mfma_f32_16x16x32_bf16 v[46:49], v[158:161], v[198:201], v[46:49]
	v_mfma_f32_16x16x32_bf16 v[42:45], v[166:169], v[198:201], v[42:45]
	v_mfma_f32_16x16x32_bf16 v[30:33], v[158:161], v[210:213], v[30:33]
	v_mfma_f32_16x16x32_bf16 v[26:29], v[166:169], v[210:213], v[26:29]
	v_mfma_f32_16x16x32_bf16 v[14:17], v[158:161], v[218:221], v[14:17]
	v_mfma_f32_16x16x32_bf16 v[10:13], v[166:169], v[218:221], v[10:13]
	s_setprio 0
	s_setprio 1
	v_mfma_f32_16x16x32_bf16 v[54:57], v[170:173], v[186:189], v[54:57]
	v_mfma_f32_16x16x32_bf16 v[50:53], v[178:181], v[186:189], v[50:53]
	v_mfma_f32_16x16x32_bf16 v[38:41], v[170:173], v[194:197], v[38:41]
	v_mfma_f32_16x16x32_bf16 v[34:37], v[178:181], v[194:197], v[34:37]
	v_mfma_f32_16x16x32_bf16 v[22:25], v[170:173], v[206:209], v[22:25]
	v_mfma_f32_16x16x32_bf16 v[18:21], v[178:181], v[206:209], v[18:21]
	v_mfma_f32_16x16x32_bf16 v[6:9], v[170:173], v[214:217], v[6:9]
	v_mfma_f32_16x16x32_bf16 v[2:5], v[178:181], v[214:217], v[2:5]
	v_mfma_f32_16x16x32_bf16 v[54:57], v[174:177], v[190:193], v[54:57]
	v_mfma_f32_16x16x32_bf16 v[50:53], v[182:185], v[190:193], v[50:53]
	v_mfma_f32_16x16x32_bf16 v[38:41], v[174:177], v[198:201], v[38:41]
	v_mfma_f32_16x16x32_bf16 v[34:37], v[182:185], v[198:201], v[34:37]
	v_mfma_f32_16x16x32_bf16 v[22:25], v[174:177], v[210:213], v[22:25]
	v_mfma_f32_16x16x32_bf16 v[18:21], v[182:185], v[210:213], v[18:21]
	v_mfma_f32_16x16x32_bf16 v[6:9], v[174:177], v[218:221], v[6:9]
	v_mfma_f32_16x16x32_bf16 v[2:5], v[182:185], v[218:221], v[2:5]
	s_setprio 0
	s_barrier
	s_add_i32 s68, s68, 2
	s_add_u32 s42, s42, 0x100
	s_addc_u32 s43, s43, 0
	s_add_u32 s66, s66, 0x100
	s_addc_u32 s67, s67, 0
	s_cmp_gt_u32 s68, 13

.LBB0_1007:
	s_add_u32 s10, s56, 0x3500000
	s_addc_u32 s11, s57, 0
	s_add_u32 s12, s56, 0x5d00000
	s_addc_u32 s13, s57, 0
	s_add_u32 s20, s56, 0x8500000
	s_addc_u32 s21, s57, 0
	s_add_u32 s22, s56, 0xad00000
	s_addc_u32 s23, s57, 0
	s_add_u32 s26, s56, 0xd500000
	s_addc_u32 s27, s57, 0
	s_lshl_b32 s6, s6, 5
	s_waitcnt lgkmcnt(0)
	s_mov_b64 s[36:37], 0x80
	s_and_b32 s78, s6, 0x60
	s_add_i32 m0, s73, 0x18000
	v_lshl_add_u64 v[8:9], v[8:9], 0, s[36:37]
	s_lshl_b32 s77, s14, 6
	s_lshl_b32 s17, s14, 13
	s_lshl_b32 s6, s78, 7
	s_waitcnt vmcnt(2)
	s_barrier
	global_load_lds_dwordx4 v[8:9], off
	v_lshl_add_u64 v[6:7], v[6:7], 0, s[36:37]
	s_add_i32 m0, s73, 0x1a000
	s_add_i32 s79, s73, 0x8000
	s_add_i32 s80, s73, 0xa000
	global_load_lds_dwordx4 v[6:7], off
	v_lshl_add_u64 v[2:3], v[2:3], 0, s[36:37]
	s_mov_b32 m0, s79
	s_add_u32 s14, s66, 0x40080
	global_load_lds_dwordx4 v[2:3], off
	v_lshl_add_u64 v[2:3], v[4:5], 0, s[36:37]
	s_mov_b32 m0, s80
	s_addc_u32 s15, s67, 0
	global_load_lds_dwordx4 v[2:3], off
	s_add_i32 m0, s73, 0x1c000
	v_lshl_add_u64 v[2:3], s[14:15], 0, v[150:151]
	global_load_lds_dwordx4 v[2:3], off
	v_lshl_add_u64 v[2:3], s[14:15], 0, v[146:147]
	s_add_i32 m0, s73, 0x1e000
	v_bfe_u32 v170, v0, 4, 2
	global_load_lds_dwordx4 v[2:3], off
	s_sext_i32_i16 s16, s4
	v_and_b32_e32 v1, 15, v0
	v_lshlrev_b32_e32 v3, 4, v170
	v_lshlrev_b32_e32 v5, 2, v0
	v_lshlrev_b32_e32 v6, 6, v0
	s_movk_i32 s4, 0x3c0
	v_lshl_or_b32 v4, v1, 6, v3
	v_and_b32_e32 v5, 32, v5
	v_and_or_b32 v3, v6, s4, v3
	v_bitop3_b32 v171, s6, v3, v5 bitop3:0xf6
	v_lshlrev_b32_e32 v3, 8, v0
	v_bitop3_b32 v4, v4, s17, v5 bitop3:0xde
	s_waitcnt vmcnt(6)
	s_cmpk_lt_u32 s5, 0x100
	v_and_b32_e32 v3, 0x18000, v3
	v_lshlrev_b32_e32 v5, 11, v12
	v_lshlrev_b32_e32 v2, 3, v170
	s_cselect_b64 s[38:39], -1, 0
	v_readlane_b32 s4, v249, 2
	v_or3_b32 v3, v10, v3, v5
	s_add_i32 s82, 0, 0x10000
	s_add_i32 s83, 0, 0x14000
	s_ashr_i32 s81, s4, 31
	v_add_u32_e32 v156, v3, v11
	v_mov_b32_e32 v157, v155
	v_add3_u32 v158, v13, v10, v11
	v_mov_b32_e32 v159, v155
	v_mov_b64_e32 v[160:161], 0x640
	v_mov_b64_e32 v[162:163], 0x63f
	v_add_u32_e32 v172, s82, v171
	v_add_u32_e32 v173, s83, v171
	v_add_u32_e32 v174, 0, v4
	s_lshl_b32 s85, s78, 2
	v_lshlrev_b32_e32 v154, 2, v2
	s_mov_b32 s86, 0x4f000
	s_mov_b32 s87, 0
	s_barrier
	v_readlane_b32 s5, v249, 3
	s_mov_b32 s100, 1
	s_branch .LBB0_1010

.LBB0_1012:
	s_add_u32 s48, s96, s44
	s_addc_u32 s49, s97, s45
	s_and_b64 s[14:15], s[4:5], exec
	s_cselect_b32 s6, s49, s65
	s_cselect_b32 s14, s48, s64
	s_add_u32 s50, s3, s46
	s_addc_u32 s51, s35, s47
	s_and_b64 s[18:19], s[4:5], exec
	s_cselect_b32 s15, s51, s67
	s_cselect_b32 s17, s50, s66
	s_add_u32 s64, s64, 0x40080
	s_addc_u32 s65, s65, 0
	s_add_u32 s18, s66, 0x100
	s_addc_u32 s19, s67, 0
	s_mov_b32 s24, -2
	s_waitcnt vmcnt(0)
	ds_read_b128 v[130:133], v172
	ds_read_b128 v[134:137], v172 offset:1024
	ds_read_b128 v[138:141], v172 offset:2048
	ds_read_b128 v[142:145], v172 offset:3072
	ds_read_b128 v[164:167], v173
	ds_read_b128 v[176:179], v173 offset:1024
	ds_read_b128 v[180:183], v173 offset:2048
	ds_read_b128 v[184:187], v173 offset:3072
	s_add_u32 s25, s64, 0xfffc0080
	s_addc_u32 s28, s65, -1
	s_cmp_eq_u32 s24, 12
	s_cselect_b32 s69, s6, s28
	s_cselect_b32 s68, s14, s25
	s_cselect_b32 s67, s15, s19
	s_cselect_b32 s66, s17, s18
	v_lshl_add_u64 v[168:169], s[64:65], 0, v[156:157]
	s_add_i32 m0, s73, 0xc000
	ds_read_b128 v[188:191], v174
	ds_read_b128 v[192:195], v174 offset:1024
	ds_read_b128 v[196:199], v174 offset:2048
	ds_read_b128 v[200:203], v174 offset:3072
	ds_read_b128 v[206:209], v174 offset:4096
	ds_read_b128 v[210:213], v174 offset:5120
	ds_read_b128 v[214:217], v174 offset:6144
	ds_read_b128 v[218:221], v174 offset:7168
	global_load_lds_dwordx4 v[168:169], off
	v_lshl_add_u64 v[168:169], s[64:65], 0, v[158:159]
	s_add_i32 m0, s73, 0xe000
	s_nop 0
	global_load_lds_dwordx4 v[168:169], off
	s_waitcnt vmcnt(24)
	s_cmp_eq_u32 s100, 0
	s_cbranch_scc1 .Lrd_1010_a
	s_waitcnt vmcnt(8)
.Lrd_1010_a:
	s_waitcnt lgkmcnt(0)
	s_barrier
	s_setprio 1
	s_waitcnt lgkmcnt(0)
	v_mfma_f32_16x16x32_bf16 v[126:129], v[130:133], v[188:191], 0
	v_mfma_f32_16x16x32_bf16 v[122:125], v[138:141], v[188:191], 0
	v_mfma_f32_16x16x32_bf16 v[110:113], v[130:133], v[196:199], 0
	v_mfma_f32_16x16x32_bf16 v[106:109], v[138:141], v[196:199], 0
	v_mfma_f32_16x16x32_bf16 v[94:97], v[130:133], v[206:209], 0
	v_mfma_f32_16x16x32_bf16 v[90:93], v[138:141], v[206:209], 0
	v_mfma_f32_16x16x32_bf16 v[78:81], v[130:133], v[214:217], 0
	v_mfma_f32_16x16x32_bf16 v[74:77], v[138:141], v[214:217], 0
	v_mfma_f32_16x16x32_bf16 v[126:129], v[134:137], v[192:195], v[126:129]
	v_mfma_f32_16x16x32_bf16 v[122:125], v[142:145], v[192:195], v[122:125]
	v_mfma_f32_16x16x32_bf16 v[110:113], v[134:137], v[200:203], v[110:113]
	v_mfma_f32_16x16x32_bf16 v[106:109], v[142:145], v[200:203], v[106:109]
	v_mfma_f32_16x16x32_bf16 v[94:97], v[134:137], v[210:213], v[94:97]
	v_mfma_f32_16x16x32_bf16 v[90:93], v[142:145], v[210:213], v[90:93]
	v_mfma_f32_16x16x32_bf16 v[78:81], v[134:137], v[218:221], v[78:81]
	v_mfma_f32_16x16x32_bf16 v[74:77], v[142:145], v[218:221], v[74:77]
	s_setprio 0
	s_setprio 1
	v_mfma_f32_16x16x32_bf16 v[118:121], v[164:167], v[188:191], 0
	v_mfma_f32_16x16x32_bf16 v[114:117], v[180:183], v[188:191], 0
	v_mfma_f32_16x16x32_bf16 v[102:105], v[164:167], v[196:199], 0
	v_mfma_f32_16x16x32_bf16 v[98:101], v[180:183], v[196:199], 0
	v_mfma_f32_16x16x32_bf16 v[86:89], v[164:167], v[206:209], 0
	v_mfma_f32_16x16x32_bf16 v[82:85], v[180:183], v[206:209], 0
	v_mfma_f32_16x16x32_bf16 v[70:73], v[164:167], v[214:217], 0
	v_mfma_f32_16x16x32_bf16 v[66:69], v[180:183], v[214:217], 0
	v_mfma_f32_16x16x32_bf16 v[118:121], v[176:179], v[192:195], v[118:121]
	v_mfma_f32_16x16x32_bf16 v[114:117], v[184:187], v[192:195], v[114:117]
	v_mfma_f32_16x16x32_bf16 v[102:105], v[176:179], v[200:203], v[102:105]
	v_mfma_f32_16x16x32_bf16 v[98:101], v[184:187], v[200:203], v[98:101]
	v_mfma_f32_16x16x32_bf16 v[86:89], v[176:179], v[210:213], v[86:89]
	v_mfma_f32_16x16x32_bf16 v[82:85], v[184:187], v[210:213], v[82:85]
	v_mfma_f32_16x16x32_bf16 v[70:73], v[176:179], v[218:221], v[70:73]
	v_mfma_f32_16x16x32_bf16 v[66:69], v[184:187], v[218:221], v[66:69]
	s_setprio 0
	s_barrier
	s_add_i32 s25, s82, s70
	v_lshl_add_u64 v[168:169], s[66:67], 0, v[150:151]
	s_mov_b32 m0, s25
	ds_read_b128 v[188:191], v174 offset:16384
	ds_read_b128 v[192:195], v174 offset:17408
	ds_read_b128 v[196:199], v174 offset:18432
	ds_read_b128 v[200:203], v174 offset:19456
	ds_read_b128 v[206:209], v174 offset:20480
	ds_read_b128 v[210:213], v174 offset:21504
	ds_read_b128 v[214:217], v174 offset:22528
	ds_read_b128 v[218:221], v174 offset:23552
	global_load_lds_dwordx4 v[168:169], off
	s_add_i32 m0, s25, 0x2000
	s_add_u32 s28, s66, 0x40000
	v_lshl_add_u64 v[222:223], s[66:67], 0, v[146:147]
	s_addc_u32 s29, s67, 0
	s_add_i32 s25, s83, s70
	global_load_lds_dwordx4 v[222:223], off
	v_lshl_add_u64 v[224:225], s[28:29], 0, v[150:151]
	s_mov_b32 m0, s25
	v_lshl_add_u64 v[226:227], s[68:69], 0, v[148:149]
	global_load_lds_dwordx4 v[224:225], off
	v_lshl_add_u64 v[224:225], s[28:29], 0, v[146:147]
	s_add_i32 m0, s25, 0x2000
	s_nop 0
	global_load_lds_dwordx4 v[224:225], off
	v_lshl_add_u64 v[224:225], s[68:69], 0, v[152:153]
	s_mov_b32 m0, s73
	s_nop 0
	global_load_lds_dwordx4 v[224:225], off
	s_mov_b32 m0, s74
	s_nop 0
	global_load_lds_dwordx4 v[226:227], off
	s_waitcnt vmcnt(24)
	s_cmp_eq_u32 s100, 0
	s_cbranch_scc1 .Lrd_1010_b
	s_waitcnt vmcnt(8)
.Lrd_1010_b:
	s_mov_b32 s100, 0
	s_waitcnt lgkmcnt(0)
	s_barrier
	s_setprio 1
	s_waitcnt lgkmcnt(0)
	v_mfma_f32_16x16x32_bf16 v[62:65], v[130:133], v[188:191], 0
	v_mfma_f32_16x16x32_bf16 v[58:61], v[138:141], v[188:191], 0
	v_mfma_f32_16x16x32_bf16 v[46:49], v[130:133], v[196:199], 0
	v_mfma_f32_16x16x32_bf16 v[42:45], v[138:141], v[196:199], 0
	v_mfma_f32_16x16x32_bf16 v[30:33], v[130:133], v[206:209], 0
	v_mfma_f32_16x16x32_bf16 v[26:29], v[138:141], v[206:209], 0
	v_mfma_f32_16x16x32_bf16 v[14:17], v[130:133], v[214:217], 0
	v_mfma_f32_16x16x32_bf16 v[10:13], v[138:141], v[214:217], 0
	v_mfma_f32_16x16x32_bf16 v[62:65], v[134:137], v[192:195], v[62:65]
	v_mfma_f32_16x16x32_bf16 v[58:61], v[142:145], v[192:195], v[58:61]
	v_mfma_f32_16x16x32_bf16 v[46:49], v[134:137], v[200:203], v[46:49]
	v_mfma_f32_16x16x32_bf16 v[42:45], v[142:145], v[200:203], v[42:45]
	v_mfma_f32_16x16x32_bf16 v[30:33], v[134:137], v[210:213], v[30:33]
	v_mfma_f32_16x16x32_bf16 v[26:29], v[142:145], v[210:213], v[26:29]
	v_mfma_f32_16x16x32_bf16 v[14:17], v[134:137], v[218:221], v[14:17]
	v_mfma_f32_16x16x32_bf16 v[10:13], v[142:145], v[218:221], v[10:13]
	s_setprio 0
	s_setprio 1
	v_mfma_f32_16x16x32_bf16 v[54:57], v[164:167], v[188:191], 0
	v_mfma_f32_16x16x32_bf16 v[50:53], v[180:183], v[188:191], 0
	v_mfma_f32_16x16x32_bf16 v[38:41], v[164:167], v[196:199], 0
	v_mfma_f32_16x16x32_bf16 v[34:37], v[180:183], v[196:199], 0
	v_mfma_f32_16x16x32_bf16 v[22:25], v[164:167], v[206:209], 0
	v_mfma_f32_16x16x32_bf16 v[18:21], v[180:183], v[206:209], 0
	v_mfma_f32_16x16x32_bf16 v[6:9], v[164:167], v[214:217], 0
	v_mfma_f32_16x16x32_bf16 v[2:5], v[180:183], v[214:217], 0
	v_mfma_f32_16x16x32_bf16 v[54:57], v[176:179], v[192:195], v[54:57]
	v_mfma_f32_16x16x32_bf16 v[50:53], v[184:187], v[192:195], v[50:53]
	v_mfma_f32_16x16x32_bf16 v[38:41], v[176:179], v[200:203], v[38:41]
	v_mfma_f32_16x16x32_bf16 v[34:37], v[184:187], v[200:203], v[34:37]
	v_mfma_f32_16x16x32_bf16 v[22:25], v[176:179], v[210:213], v[22:25]
	v_mfma_f32_16x16x32_bf16 v[18:21], v[184:187], v[210:213], v[18:21]
	v_mfma_f32_16x16x32_bf16 v[6:9], v[176:179], v[218:221], v[6:9]
	v_mfma_f32_16x16x32_bf16 v[2:5], v[184:187], v[218:221], v[2:5]
	s_setprio 0
	s_barrier
	s_add_i32 s25, 0, 0x18000
	s_add_i32 s30, 0, 0x1c000
	v_add_u32_e32 v142, s25, v171
	v_add_u32_e32 v175, s30, v171
	ds_read_b128 v[130:133], v142
	ds_read_b128 v[134:137], v142 offset:1024
	ds_read_b128 v[138:141], v142 offset:2048
	ds_read_b128 v[142:145], v142 offset:3072
	ds_read_b128 v[164:167], v175
	ds_read_b128 v[176:179], v175 offset:1024
	ds_read_b128 v[180:183], v175 offset:2048
	ds_read_b128 v[184:187], v175 offset:3072
	s_add_u32 s28, s68, 0x40000
	s_addc_u32 s29, s69, 0
	s_mov_b32 m0, s75
	v_lshl_add_u64 v[228:229], s[28:29], 0, v[152:153]
	ds_read_b128 v[188:191], v174 offset:32768
	ds_read_b128 v[192:195], v174 offset:33792
	ds_read_b128 v[196:199], v174 offset:34816
	ds_read_b128 v[200:203], v174 offset:35840
	ds_read_b128 v[206:209], v174 offset:36864
	ds_read_b128 v[210:213], v174 offset:37888
	ds_read_b128 v[214:217], v174 offset:38912
	ds_read_b128 v[218:221], v174 offset:39936
	global_load_lds_dwordx4 v[228:229], off
	v_lshl_add_u64 v[228:229], s[28:29], 0, v[148:149]
	s_mov_b32 m0, s76
	s_nop 0
	global_load_lds_dwordx4 v[228:229], off
	s_waitcnt vmcnt(8)
	s_waitcnt lgkmcnt(0)
	s_barrier
	s_setprio 1
	s_waitcnt lgkmcnt(0)
	v_mfma_f32_16x16x32_bf16 v[126:129], v[130:133], v[188:191], v[126:129]
	v_mfma_f32_16x16x32_bf16 v[122:125], v[138:141], v[188:191], v[122:125]
	v_mfma_f32_16x16x32_bf16 v[110:113], v[130:133], v[196:199], v[110:113]
	v_mfma_f32_16x16x32_bf16 v[106:109], v[138:141], v[196:199], v[106:109]
	v_mfma_f32_16x16x32_bf16 v[94:97], v[130:133], v[206:209], v[94:97]
	v_mfma_f32_16x16x32_bf16 v[90:93], v[138:141], v[206:209], v[90:93]
	v_mfma_f32_16x16x32_bf16 v[78:81], v[130:133], v[214:217], v[78:81]
	v_mfma_f32_16x16x32_bf16 v[74:77], v[138:141], v[214:217], v[74:77]
	v_mfma_f32_16x16x32_bf16 v[126:129], v[134:137], v[192:195], v[126:129]
	v_mfma_f32_16x16x32_bf16 v[122:125], v[142:145], v[192:195], v[122:125]
	v_mfma_f32_16x16x32_bf16 v[110:113], v[134:137], v[200:203], v[110:113]
	v_mfma_f32_16x16x32_bf16 v[106:109], v[142:145], v[200:203], v[106:109]
	v_mfma_f32_16x16x32_bf16 v[94:97], v[134:137], v[210:213], v[94:97]
	v_mfma_f32_16x16x32_bf16 v[90:93], v[142:145], v[210:213], v[90:93]
	v_mfma_f32_16x16x32_bf16 v[78:81], v[134:137], v[218:221], v[78:81]
	v_mfma_f32_16x16x32_bf16 v[74:77], v[142:145], v[218:221], v[74:77]
	s_setprio 0
	s_setprio 1
	v_mfma_f32_16x16x32_bf16 v[118:121], v[164:167], v[188:191], v[118:121]
	v_mfma_f32_16x16x32_bf16 v[114:117], v[180:183], v[188:191], v[114:117]
	v_mfma_f32_16x16x32_bf16 v[102:105], v[164:167], v[196:199], v[102:105]
	v_mfma_f32_16x16x32_bf16 v[98:101], v[180:183], v[196:199], v[98:101]
	v_mfma_f32_16x16x32_bf16 v[86:89], v[164:167], v[206:209], v[86:89]
	v_mfma_f32_16x16x32_bf16 v[82:85], v[180:183], v[206:209], v[82:85]
	v_mfma_f32_16x16x32_bf16 v[70:73], v[164:167], v[214:217], v[70:73]
	v_mfma_f32_16x16x32_bf16 v[66:69], v[180:183], v[214:217], v[66:69]
	v_mfma_f32_16x16x32_bf16 v[118:121], v[176:179], v[192:195], v[118:121]
	v_mfma_f32_16x16x32_bf16 v[114:117], v[184:187], v[192:195], v[114:117]
	v_mfma_f32_16x16x32_bf16 v[102:105], v[176:179], v[200:203], v[102:105]
	v_mfma_f32_16x16x32_bf16 v[98:101], v[184:187], v[200:203], v[98:101]
	v_mfma_f32_16x16x32_bf16 v[86:89], v[176:179], v[210:213], v[86:89]
	v_mfma_f32_16x16x32_bf16 v[82:85], v[184:187], v[210:213], v[82:85]
	v_mfma_f32_16x16x32_bf16 v[70:73], v[176:179], v[218:221], v[70:73]
	v_mfma_f32_16x16x32_bf16 v[66:69], v[184:187], v[218:221], v[66:69]
	s_setprio 0
	s_barrier
	s_add_i32 s25, s25, s70
	v_lshl_add_u64 v[168:169], v[168:169], 0, s[36:37]
	s_mov_b32 m0, s25
	ds_read_b128 v[188:191], v174 offset:49152
	ds_read_b128 v[192:195], v174 offset:50176
	ds_read_b128 v[196:199], v174 offset:51200
	ds_read_b128 v[200:203], v174 offset:52224
	ds_read_b128 v[206:209], v174 offset:53248
	ds_read_b128 v[210:213], v174 offset:54272
	ds_read_b128 v[214:217], v174 offset:55296
	ds_read_b128 v[218:221], v174 offset:56320
	global_load_lds_dwordx4 v[168:169], off
	s_add_i32 m0, s25, 0x2000
	s_add_u32 s28, s66, 0x40080
	v_lshl_add_u64 v[168:169], v[222:223], 0, s[36:37]
	s_addc_u32 s29, s67, 0
	s_add_i32 s25, s30, s70
	global_load_lds_dwordx4 v[168:169], off
	v_lshl_add_u64 v[168:169], s[28:29], 0, v[150:151]
	s_mov_b32 m0, s25
	s_nop 0
	global_load_lds_dwordx4 v[168:169], off
	v_lshl_add_u64 v[168:169], s[28:29], 0, v[146:147]
	s_add_i32 m0, s25, 0x2000
	s_nop 0
	global_load_lds_dwordx4 v[168:169], off
	v_lshl_add_u64 v[168:169], v[224:225], 0, s[36:37]
	s_mov_b32 m0, s79
	s_nop 0
	global_load_lds_dwordx4 v[168:169], off
	v_lshl_add_u64 v[168:169], v[226:227], 0, s[36:37]
	s_mov_b32 m0, s80
	s_nop 0
	global_load_lds_dwordx4 v[168:169], off
	s_waitcnt vmcnt(8)
	s_waitcnt lgkmcnt(0)
	s_barrier
	s_setprio 1
	s_waitcnt lgkmcnt(0)
	v_mfma_f32_16x16x32_bf16 v[62:65], v[130:133], v[188:191], v[62:65]
	v_mfma_f32_16x16x32_bf16 v[58:61], v[138:141], v[188:191], v[58:61]
	v_mfma_f32_16x16x32_bf16 v[46:49], v[130:133], v[196:199], v[46:49]
	v_mfma_f32_16x16x32_bf16 v[42:45], v[138:141], v[196:199], v[42:45]
	v_mfma_f32_16x16x32_bf16 v[30:33], v[130:133], v[206:209], v[30:33]
	v_mfma_f32_16x16x32_bf16 v[26:29], v[138:141], v[206:209], v[26:29]
	v_mfma_f32_16x16x32_bf16 v[14:17], v[130:133], v[214:217], v[14:17]
	v_mfma_f32_16x16x32_bf16 v[10:13], v[138:141], v[214:217], v[10:13]
	v_mfma_f32_16x16x32_bf16 v[62:65], v[134:137], v[192:195], v[62:65]
	v_mfma_f32_16x16x32_bf16 v[58:61], v[142:145], v[192:195], v[58:61]
	v_mfma_f32_16x16x32_bf16 v[46:49], v[134:137], v[200:203], v[46:49]
	v_mfma_f32_16x16x32_bf16 v[42:45], v[142:145], v[200:203], v[42:45]
	v_mfma_f32_16x16x32_bf16 v[30:33], v[134:137], v[210:213], v[30:33]
	v_mfma_f32_16x16x32_bf16 v[26:29], v[142:145], v[210:213], v[26:29]
	v_mfma_f32_16x16x32_bf16 v[14:17], v[134:137], v[218:221], v[14:17]
	v_mfma_f32_16x16x32_bf16 v[10:13], v[142:145], v[218:221], v[10:13]
	s_setprio 0
	s_setprio 1
	v_mfma_f32_16x16x32_bf16 v[54:57], v[164:167], v[188:191], v[54:57]
	v_mfma_f32_16x16x32_bf16 v[50:53], v[180:183], v[188:191], v[50:53]
	v_mfma_f32_16x16x32_bf16 v[38:41], v[164:167], v[196:199], v[38:41]
	v_mfma_f32_16x16x32_bf16 v[34:37], v[180:183], v[196:199], v[34:37]
	v_mfma_f32_16x16x32_bf16 v[22:25], v[164:167], v[206:209], v[22:25]
	v_mfma_f32_16x16x32_bf16 v[18:21], v[180:183], v[206:209], v[18:21]
	v_mfma_f32_16x16x32_bf16 v[6:9], v[164:167], v[214:217], v[6:9]
	v_mfma_f32_16x16x32_bf16 v[2:5], v[180:183], v[214:217], v[2:5]
	v_mfma_f32_16x16x32_bf16 v[54:57], v[176:179], v[192:195], v[54:57]
	v_mfma_f32_16x16x32_bf16 v[50:53], v[184:187], v[192:195], v[50:53]
	v_mfma_f32_16x16x32_bf16 v[38:41], v[176:179], v[200:203], v[38:41]
	v_mfma_f32_16x16x32_bf16 v[34:37], v[184:187], v[200:203], v[34:37]
	v_mfma_f32_16x16x32_bf16 v[22:25], v[176:179], v[210:213], v[22:25]
	v_mfma_f32_16x16x32_bf16 v[18:21], v[184:187], v[210:213], v[18:21]
	v_mfma_f32_16x16x32_bf16 v[6:9], v[176:179], v[218:221], v[6:9]
	v_mfma_f32_16x16x32_bf16 v[2:5], v[184:187], v[218:221], v[2:5]
	s_setprio 0
	s_barrier
	s_add_i32 s24, s24, 2
	s_add_u32 s64, s64, 0x100
	s_addc_u32 s65, s65, 0
	s_add_u32 s18, s18, 0x100
	s_addc_u32 s19, s19, 0
	s_cmp_gt_u32 s24, 13

.LBB0_1613:
	s_lshl_b32 s8, s8, 5
	s_lshl_b32 s40, s9, 6
	s_lshl_b32 s14, s9, 13
	s_and_b32 s41, s8, 0x60
	s_mov_b64 s[8:9], 0x80
	s_add_i32 m0, s19, 0x18000
	v_lshl_add_u64 v[8:9], v[8:9], 0, s[8:9]
	s_lshl_b32 s15, s41, 7
	s_waitcnt vmcnt(2)
	s_barrier
	global_load_lds_dwordx4 v[8:9], off
	v_lshl_add_u64 v[6:7], v[6:7], 0, s[8:9]
	s_add_i32 m0, s19, 0x1a000
	s_add_i32 s42, s19, 0x8000
	s_add_i32 s43, s19, 0xa000
	global_load_lds_dwordx4 v[6:7], off
	v_lshl_add_u64 v[2:3], v[2:3], 0, s[8:9]
	s_mov_b32 m0, s42
	s_add_u32 s10, s30, 0x40080
	global_load_lds_dwordx4 v[2:3], off
	v_lshl_add_u64 v[2:3], v[4:5], 0, s[8:9]
	s_mov_b32 m0, s43
	s_addc_u32 s11, s31, 0
	global_load_lds_dwordx4 v[2:3], off
	s_add_i32 m0, s19, 0x1c000
	v_lshl_add_u64 v[2:3], s[10:11], 0, v[134:135]
	global_load_lds_dwordx4 v[2:3], off
	v_lshl_add_u64 v[2:3], s[10:11], 0, v[130:131]
	s_add_i32 m0, s19, 0x1e000
	v_bfe_u32 v148, v0, 4, 2
	global_load_lds_dwordx4 v[2:3], off
	s_sext_i32_i8 s48, s4
	v_and_b32_e32 v1, 15, v0
	v_lshlrev_b32_e32 v2, 4, v148
	v_lshlrev_b32_e32 v4, 2, v0
	v_lshlrev_b32_e32 v5, 6, v0
	s_movk_i32 s4, 0x3c0
	v_lshl_or_b32 v3, v1, 6, v2
	v_and_b32_e32 v4, 32, v4
	v_and_or_b32 v2, v5, s4, v2
	v_bitop3_b32 v149, s15, v2, v4 bitop3:0xf6
	v_lshlrev_b32_e32 v2, 8, v0
	v_bitop3_b32 v3, v3, s14, v4 bitop3:0xde
	s_waitcnt vmcnt(6)
	s_cmpk_lt_u32 s5, 0x100
	v_and_b32_e32 v2, 0x18000, v2
	v_lshlrev_b32_e32 v4, 11, v12
	s_cselect_b64 s[10:11], -1, 0
	v_readlane_b32 s4, v249, 2
	v_or3_b32 v2, v10, v2, v4
	s_add_i32 s45, 0, 0x10000
	s_add_i32 s46, 0, 0x14000
	s_ashr_i32 s44, s4, 31
	v_add_u32_e32 v138, v2, v11
	v_mov_b32_e32 v139, v135
	v_add3_u32 v140, v13, v10, v11
	v_mov_b32_e32 v141, v135
	v_mov_b64_e32 v[142:143], 0x500
	v_mov_b64_e32 v[144:145], 0x4ff
	v_add_u32_e32 v150, s45, v149
	v_add_u32_e32 v151, s46, v149
	v_add_u32_e32 v152, 0, v3
	s_barrier
	v_readlane_b32 s5, v249, 3
	s_mov_b32 s100, 1
	s_branch .LBB0_1616

.LBB0_1618:
	s_add_u32 s24, s96, s20
	s_addc_u32 s25, s97, s21
	s_and_b64 s[14:15], s[4:5], exec
	s_cselect_b32 s14, s25, s29
	s_cselect_b32 s15, s24, s28
	s_add_u32 s26, s2, s22
	s_addc_u32 s27, s3, s23
	s_and_b64 s[36:37], s[4:5], exec
	s_cselect_b32 s17, s27, s31
	s_cselect_b32 s49, s26, s30
	s_add_u32 s28, s28, 0x40080
	s_addc_u32 s29, s29, 0
	s_add_u32 s50, s30, 0x100
	s_addc_u32 s51, s31, 0
	s_mov_b32 s62, -2
	ds_read_b128 v[154:157], v150
	ds_read_b128 v[158:161], v150 offset:1024
	ds_read_b128 v[162:165], v150 offset:2048
	ds_read_b128 v[166:169], v150 offset:3072
	ds_read_b128 v[170:173], v151
	ds_read_b128 v[174:177], v151 offset:1024
	ds_read_b128 v[178:181], v151 offset:2048
	ds_read_b128 v[182:185], v151 offset:3072
	s_add_u32 s30, s28, 0xfffc0080
	s_addc_u32 s31, s29, -1
	s_cmp_eq_u32 s62, 12
	s_cselect_b32 s37, s14, s31
	s_cselect_b32 s36, s15, s30
	s_cselect_b32 s31, s17, s51
	s_cselect_b32 s30, s49, s50
	v_lshl_add_u64 v[146:147], s[28:29], 0, v[138:139]
	s_add_i32 m0, s19, 0xc000
	ds_read_b128 v[186:189], v152
	ds_read_b128 v[190:193], v152 offset:1024
	ds_read_b128 v[194:197], v152 offset:2048
	ds_read_b128 v[198:201], v152 offset:3072
	ds_read_b128 v[206:209], v152 offset:4096
	ds_read_b128 v[210:213], v152 offset:5120
	ds_read_b128 v[214:217], v152 offset:6144
	ds_read_b128 v[218:221], v152 offset:7168
	global_load_lds_dwordx4 v[146:147], off
	v_lshl_add_u64 v[146:147], s[28:29], 0, v[140:141]
	s_add_i32 m0, s19, 0xe000
	s_nop 0
	global_load_lds_dwordx4 v[146:147], off
	s_waitcnt vmcnt(24)
	s_cmp_eq_u32 s100, 0
	s_cbranch_scc1 .Lrd_1616_a
	s_waitcnt vmcnt(8)
.Lrd_1616_a:
	s_waitcnt lgkmcnt(0)
	s_barrier
	s_setprio 1
	s_waitcnt lgkmcnt(0)
	v_mfma_f32_16x16x32_bf16 v[126:129], v[154:157], v[186:189], 0
	v_mfma_f32_16x16x32_bf16 v[122:125], v[162:165], v[186:189], 0
	v_mfma_f32_16x16x32_bf16 v[110:113], v[154:157], v[194:197], 0
	v_mfma_f32_16x16x32_bf16 v[106:109], v[162:165], v[194:197], 0
	v_mfma_f32_16x16x32_bf16 v[94:97], v[154:157], v[206:209], 0
	v_mfma_f32_16x16x32_bf16 v[90:93], v[162:165], v[206:209], 0
	v_mfma_f32_16x16x32_bf16 v[78:81], v[154:157], v[214:217], 0
	v_mfma_f32_16x16x32_bf16 v[74:77], v[162:165], v[214:217], 0
	v_mfma_f32_16x16x32_bf16 v[126:129], v[158:161], v[190:193], v[126:129]
	v_mfma_f32_16x16x32_bf16 v[122:125], v[166:169], v[190:193], v[122:125]
	v_mfma_f32_16x16x32_bf16 v[110:113], v[158:161], v[198:201], v[110:113]
	v_mfma_f32_16x16x32_bf16 v[106:109], v[166:169], v[198:201], v[106:109]
	v_mfma_f32_16x16x32_bf16 v[94:97], v[158:161], v[210:213], v[94:97]
	v_mfma_f32_16x16x32_bf16 v[90:93], v[166:169], v[210:213], v[90:93]
	v_mfma_f32_16x16x32_bf16 v[78:81], v[158:161], v[218:221], v[78:81]
	v_mfma_f32_16x16x32_bf16 v[74:77], v[166:169], v[218:221], v[74:77]
	s_setprio 0
	s_setprio 1
	v_mfma_f32_16x16x32_bf16 v[118:121], v[170:173], v[186:189], 0
	v_mfma_f32_16x16x32_bf16 v[114:117], v[178:181], v[186:189], 0
	v_mfma_f32_16x16x32_bf16 v[102:105], v[170:173], v[194:197], 0
	v_mfma_f32_16x16x32_bf16 v[98:101], v[178:181], v[194:197], 0
	v_mfma_f32_16x16x32_bf16 v[86:89], v[170:173], v[206:209], 0
	v_mfma_f32_16x16x32_bf16 v[82:85], v[178:181], v[206:209], 0
	v_mfma_f32_16x16x32_bf16 v[70:73], v[170:173], v[214:217], 0
	v_mfma_f32_16x16x32_bf16 v[66:69], v[178:181], v[214:217], 0
	v_mfma_f32_16x16x32_bf16 v[118:121], v[174:177], v[190:193], v[118:121]
	v_mfma_f32_16x16x32_bf16 v[114:117], v[182:185], v[190:193], v[114:117]
	v_mfma_f32_16x16x32_bf16 v[102:105], v[174:177], v[198:201], v[102:105]
	v_mfma_f32_16x16x32_bf16 v[98:101], v[182:185], v[198:201], v[98:101]
	v_mfma_f32_16x16x32_bf16 v[86:89], v[174:177], v[210:213], v[86:89]
	v_mfma_f32_16x16x32_bf16 v[82:85], v[182:185], v[210:213], v[82:85]
	v_mfma_f32_16x16x32_bf16 v[70:73], v[174:177], v[218:221], v[70:73]
	v_mfma_f32_16x16x32_bf16 v[66:69], v[182:185], v[218:221], v[66:69]
	s_setprio 0
	s_barrier
	s_add_i32 s63, s45, s12
	v_lshl_add_u64 v[146:147], s[30:31], 0, v[134:135]
	s_mov_b32 m0, s63
	ds_read_b128 v[186:189], v152 offset:16384
	ds_read_b128 v[190:193], v152 offset:17408
	ds_read_b128 v[194:197], v152 offset:18432
	ds_read_b128 v[198:201], v152 offset:19456
	ds_read_b128 v[206:209], v152 offset:20480
	ds_read_b128 v[210:213], v152 offset:21504
	ds_read_b128 v[214:217], v152 offset:22528
	ds_read_b128 v[218:221], v152 offset:23552
	global_load_lds_dwordx4 v[146:147], off
	s_add_i32 m0, s63, 0x2000
	s_add_u32 s64, s30, 0x40000
	v_lshl_add_u64 v[202:203], s[30:31], 0, v[130:131]
	s_addc_u32 s65, s31, 0
	s_add_i32 s63, s46, s12
	global_load_lds_dwordx4 v[202:203], off
	v_lshl_add_u64 v[222:223], s[64:65], 0, v[134:135]
	s_mov_b32 m0, s63
	v_lshl_add_u64 v[224:225], s[36:37], 0, v[132:133]
	global_load_lds_dwordx4 v[222:223], off
	v_lshl_add_u64 v[222:223], s[64:65], 0, v[130:131]
	s_add_i32 m0, s63, 0x2000
	s_nop 0
	global_load_lds_dwordx4 v[222:223], off
	v_lshl_add_u64 v[222:223], s[36:37], 0, v[136:137]
	s_mov_b32 m0, s19
	s_nop 0
	global_load_lds_dwordx4 v[222:223], off
	s_mov_b32 m0, s33
	s_nop 0
	global_load_lds_dwordx4 v[224:225], off
	s_waitcnt vmcnt(24)
	s_cmp_eq_u32 s100, 0
	s_cbranch_scc1 .Lrd_1616_b
	s_waitcnt vmcnt(8)
.Lrd_1616_b:
	s_mov_b32 s100, 0
	s_waitcnt lgkmcnt(0)
	s_barrier
	s_setprio 1
	s_waitcnt lgkmcnt(0)
	v_mfma_f32_16x16x32_bf16 v[62:65], v[154:157], v[186:189], 0
	v_mfma_f32_16x16x32_bf16 v[58:61], v[162:165], v[186:189], 0
	v_mfma_f32_16x16x32_bf16 v[46:49], v[154:157], v[194:197], 0
	v_mfma_f32_16x16x32_bf16 v[42:45], v[162:165], v[194:197], 0
	v_mfma_f32_16x16x32_bf16 v[30:33], v[154:157], v[206:209], 0
	v_mfma_f32_16x16x32_bf16 v[26:29], v[162:165], v[206:209], 0
	v_mfma_f32_16x16x32_bf16 v[14:17], v[154:157], v[214:217], 0
	v_mfma_f32_16x16x32_bf16 v[10:13], v[162:165], v[214:217], 0
	v_mfma_f32_16x16x32_bf16 v[62:65], v[158:161], v[190:193], v[62:65]
	v_mfma_f32_16x16x32_bf16 v[58:61], v[166:169], v[190:193], v[58:61]
	v_mfma_f32_16x16x32_bf16 v[46:49], v[158:161], v[198:201], v[46:49]
	v_mfma_f32_16x16x32_bf16 v[42:45], v[166:169], v[198:201], v[42:45]
	v_mfma_f32_16x16x32_bf16 v[30:33], v[158:161], v[210:213], v[30:33]
	v_mfma_f32_16x16x32_bf16 v[26:29], v[166:169], v[210:213], v[26:29]
	v_mfma_f32_16x16x32_bf16 v[14:17], v[158:161], v[218:221], v[14:17]
	v_mfma_f32_16x16x32_bf16 v[10:13], v[166:169], v[218:221], v[10:13]
	s_setprio 0
	s_setprio 1
	v_mfma_f32_16x16x32_bf16 v[54:57], v[170:173], v[186:189], 0
	v_mfma_f32_16x16x32_bf16 v[50:53], v[178:181], v[186:189], 0
	v_mfma_f32_16x16x32_bf16 v[38:41], v[170:173], v[194:197], 0
	v_mfma_f32_16x16x32_bf16 v[34:37], v[178:181], v[194:197], 0
	v_mfma_f32_16x16x32_bf16 v[22:25], v[170:173], v[206:209], 0
	v_mfma_f32_16x16x32_bf16 v[18:21], v[178:181], v[206:209], 0
	v_mfma_f32_16x16x32_bf16 v[6:9], v[170:173], v[214:217], 0
	v_mfma_f32_16x16x32_bf16 v[2:5], v[178:181], v[214:217], 0
	v_mfma_f32_16x16x32_bf16 v[54:57], v[174:177], v[190:193], v[54:57]
	v_mfma_f32_16x16x32_bf16 v[50:53], v[182:185], v[190:193], v[50:53]
	v_mfma_f32_16x16x32_bf16 v[38:41], v[174:177], v[198:201], v[38:41]
	v_mfma_f32_16x16x32_bf16 v[34:37], v[182:185], v[198:201], v[34:37]
	v_mfma_f32_16x16x32_bf16 v[22:25], v[174:177], v[210:213], v[22:25]
	v_mfma_f32_16x16x32_bf16 v[18:21], v[182:185], v[210:213], v[18:21]
	v_mfma_f32_16x16x32_bf16 v[6:9], v[174:177], v[218:221], v[6:9]
	v_mfma_f32_16x16x32_bf16 v[2:5], v[182:185], v[218:221], v[2:5]
	s_setprio 0
	s_barrier
	s_add_i32 s63, 0, 0x18000
	v_add_u32_e32 v153, s63, v149
	s_add_i32 s64, 0, 0x1c000
	ds_read_b128 v[154:157], v153
	ds_read_b128 v[158:161], v153 offset:1024
	ds_read_b128 v[162:165], v153 offset:2048
	ds_read_b128 v[166:169], v153 offset:3072
	v_add_u32_e32 v153, s64, v149
	ds_read_b128 v[170:173], v153
	ds_read_b128 v[174:177], v153 offset:1024
	ds_read_b128 v[178:181], v153 offset:2048
	ds_read_b128 v[182:185], v153 offset:3072
	s_add_u32 s36, s36, 0x40000
	s_addc_u32 s37, s37, 0
	s_mov_b32 m0, s35
	v_lshl_add_u64 v[226:227], s[36:37], 0, v[136:137]
	ds_read_b128 v[186:189], v152 offset:32768
	ds_read_b128 v[190:193], v152 offset:33792
	ds_read_b128 v[194:197], v152 offset:34816
	ds_read_b128 v[198:201], v152 offset:35840
	ds_read_b128 v[206:209], v152 offset:36864
	ds_read_b128 v[210:213], v152 offset:37888
	ds_read_b128 v[214:217], v152 offset:38912
	ds_read_b128 v[218:221], v152 offset:39936
	global_load_lds_dwordx4 v[226:227], off
	v_lshl_add_u64 v[226:227], s[36:37], 0, v[132:133]
	s_mov_b32 m0, s38
	s_nop 0
	global_load_lds_dwordx4 v[226:227], off
	s_waitcnt vmcnt(8)
	s_waitcnt lgkmcnt(0)
	s_barrier
	s_setprio 1
	s_waitcnt lgkmcnt(0)
	v_mfma_f32_16x16x32_bf16 v[126:129], v[154:157], v[186:189], v[126:129]
	v_mfma_f32_16x16x32_bf16 v[122:125], v[162:165], v[186:189], v[122:125]
	v_mfma_f32_16x16x32_bf16 v[110:113], v[154:157], v[194:197], v[110:113]
	v_mfma_f32_16x16x32_bf16 v[106:109], v[162:165], v[194:197], v[106:109]
	v_mfma_f32_16x16x32_bf16 v[94:97], v[154:157], v[206:209], v[94:97]
	v_mfma_f32_16x16x32_bf16 v[90:93], v[162:165], v[206:209], v[90:93]
	v_mfma_f32_16x16x32_bf16 v[78:81], v[154:157], v[214:217], v[78:81]
	v_mfma_f32_16x16x32_bf16 v[74:77], v[162:165], v[214:217], v[74:77]
	v_mfma_f32_16x16x32_bf16 v[126:129], v[158:161], v[190:193], v[126:129]
	v_mfma_f32_16x16x32_bf16 v[122:125], v[166:169], v[190:193], v[122:125]
	v_mfma_f32_16x16x32_bf16 v[110:113], v[158:161], v[198:201], v[110:113]
	v_mfma_f32_16x16x32_bf16 v[106:109], v[166:169], v[198:201], v[106:109]
	v_mfma_f32_16x16x32_bf16 v[94:97], v[158:161], v[210:213], v[94:97]
	v_mfma_f32_16x16x32_bf16 v[90:93], v[166:169], v[210:213], v[90:93]
	v_mfma_f32_16x16x32_bf16 v[78:81], v[158:161], v[218:221], v[78:81]
	v_mfma_f32_16x16x32_bf16 v[74:77], v[166:169], v[218:221], v[74:77]
	s_setprio 0
	s_setprio 1
	v_mfma_f32_16x16x32_bf16 v[118:121], v[170:173], v[186:189], v[118:121]
	v_mfma_f32_16x16x32_bf16 v[114:117], v[178:181], v[186:189], v[114:117]
	v_mfma_f32_16x16x32_bf16 v[102:105], v[170:173], v[194:197], v[102:105]
	v_mfma_f32_16x16x32_bf16 v[98:101], v[178:181], v[194:197], v[98:101]
	v_mfma_f32_16x16x32_bf16 v[86:89], v[170:173], v[206:209], v[86:89]
	v_mfma_f32_16x16x32_bf16 v[82:85], v[178:181], v[206:209], v[82:85]
	v_mfma_f32_16x16x32_bf16 v[70:73], v[170:173], v[214:217], v[70:73]
	v_mfma_f32_16x16x32_bf16 v[66:69], v[178:181], v[214:217], v[66:69]
	v_mfma_f32_16x16x32_bf16 v[118:121], v[174:177], v[190:193], v[118:121]
	v_mfma_f32_16x16x32_bf16 v[114:117], v[182:185], v[190:193], v[114:117]
	v_mfma_f32_16x16x32_bf16 v[102:105], v[174:177], v[198:201], v[102:105]
	v_mfma_f32_16x16x32_bf16 v[98:101], v[182:185], v[198:201], v[98:101]
	v_mfma_f32_16x16x32_bf16 v[86:89], v[174:177], v[210:213], v[86:89]
	v_mfma_f32_16x16x32_bf16 v[82:85], v[182:185], v[210:213], v[82:85]
	v_mfma_f32_16x16x32_bf16 v[70:73], v[174:177], v[218:221], v[70:73]
	v_mfma_f32_16x16x32_bf16 v[66:69], v[182:185], v[218:221], v[66:69]
	s_setprio 0
	s_barrier
	s_add_i32 s36, s63, s12
	v_lshl_add_u64 v[146:147], v[146:147], 0, s[8:9]
	s_mov_b32 m0, s36
	ds_read_b128 v[186:189], v152 offset:49152
	ds_read_b128 v[190:193], v152 offset:50176
	ds_read_b128 v[194:197], v152 offset:51200
	ds_read_b128 v[198:201], v152 offset:52224
	ds_read_b128 v[206:209], v152 offset:53248
	ds_read_b128 v[210:213], v152 offset:54272
	ds_read_b128 v[214:217], v152 offset:55296
	ds_read_b128 v[218:221], v152 offset:56320
	global_load_lds_dwordx4 v[146:147], off
	s_add_i32 m0, s36, 0x2000
	s_add_u32 s30, s30, 0x40080
	v_lshl_add_u64 v[146:147], v[202:203], 0, s[8:9]
	s_addc_u32 s31, s31, 0
	s_add_i32 s36, s64, s12
	global_load_lds_dwordx4 v[146:147], off
	v_lshl_add_u64 v[146:147], s[30:31], 0, v[134:135]
	s_mov_b32 m0, s36
	s_nop 0
	global_load_lds_dwordx4 v[146:147], off
	v_lshl_add_u64 v[146:147], s[30:31], 0, v[130:131]
	s_add_i32 m0, s36, 0x2000
	s_nop 0
	global_load_lds_dwordx4 v[146:147], off
	v_lshl_add_u64 v[146:147], v[222:223], 0, s[8:9]
	s_mov_b32 m0, s42
	s_nop 0
	global_load_lds_dwordx4 v[146:147], off
	v_lshl_add_u64 v[146:147], v[224:225], 0, s[8:9]
	s_mov_b32 m0, s43
	s_nop 0
	global_load_lds_dwordx4 v[146:147], off
	s_waitcnt vmcnt(8)
	s_waitcnt lgkmcnt(0)
	s_barrier
	s_setprio 1
	s_waitcnt lgkmcnt(0)
	v_mfma_f32_16x16x32_bf16 v[62:65], v[154:157], v[186:189], v[62:65]
	v_mfma_f32_16x16x32_bf16 v[58:61], v[162:165], v[186:189], v[58:61]
	v_mfma_f32_16x16x32_bf16 v[46:49], v[154:157], v[194:197], v[46:49]
	v_mfma_f32_16x16x32_bf16 v[42:45], v[162:165], v[194:197], v[42:45]
	v_mfma_f32_16x16x32_bf16 v[30:33], v[154:157], v[206:209], v[30:33]
	v_mfma_f32_16x16x32_bf16 v[26:29], v[162:165], v[206:209], v[26:29]
	v_mfma_f32_16x16x32_bf16 v[14:17], v[154:157], v[214:217], v[14:17]
	v_mfma_f32_16x16x32_bf16 v[10:13], v[162:165], v[214:217], v[10:13]
	v_mfma_f32_16x16x32_bf16 v[62:65], v[158:161], v[190:193], v[62:65]
	v_mfma_f32_16x16x32_bf16 v[58:61], v[166:169], v[190:193], v[58:61]
	v_mfma_f32_16x16x32_bf16 v[46:49], v[158:161], v[198:201], v[46:49]
	v_mfma_f32_16x16x32_bf16 v[42:45], v[166:169], v[198:201], v[42:45]
	v_mfma_f32_16x16x32_bf16 v[30:33], v[158:161], v[210:213], v[30:33]
	v_mfma_f32_16x16x32_bf16 v[26:29], v[166:169], v[210:213], v[26:29]
	v_mfma_f32_16x16x32_bf16 v[14:17], v[158:161], v[218:221], v[14:17]
	v_mfma_f32_16x16x32_bf16 v[10:13], v[166:169], v[218:221], v[10:13]
	s_setprio 0
	s_setprio 1
	v_mfma_f32_16x16x32_bf16 v[54:57], v[170:173], v[186:189], v[54:57]
	v_mfma_f32_16x16x32_bf16 v[50:53], v[178:181], v[186:189], v[50:53]
	v_mfma_f32_16x16x32_bf16 v[38:41], v[170:173], v[194:197], v[38:41]
	v_mfma_f32_16x16x32_bf16 v[34:37], v[178:181], v[194:197], v[34:37]
	v_mfma_f32_16x16x32_bf16 v[22:25], v[170:173], v[206:209], v[22:25]
	v_mfma_f32_16x16x32_bf16 v[18:21], v[178:181], v[206:209], v[18:21]
	v_mfma_f32_16x16x32_bf16 v[6:9], v[170:173], v[214:217], v[6:9]
	v_mfma_f32_16x16x32_bf16 v[2:5], v[178:181], v[214:217], v[2:5]
	v_mfma_f32_16x16x32_bf16 v[54:57], v[174:177], v[190:193], v[54:57]
	v_mfma_f32_16x16x32_bf16 v[50:53], v[182:185], v[190:193], v[50:53]
	v_mfma_f32_16x16x32_bf16 v[38:41], v[174:177], v[198:201], v[38:41]
	v_mfma_f32_16x16x32_bf16 v[34:37], v[182:185], v[198:201], v[34:37]
	v_mfma_f32_16x16x32_bf16 v[22:25], v[174:177], v[210:213], v[22:25]
	v_mfma_f32_16x16x32_bf16 v[18:21], v[182:185], v[210:213], v[18:21]
	v_mfma_f32_16x16x32_bf16 v[6:9], v[174:177], v[218:221], v[6:9]
	v_mfma_f32_16x16x32_bf16 v[2:5], v[182:185], v[218:221], v[2:5]
	s_setprio 0
	s_barrier
	s_add_i32 s62, s62, 2
	s_add_u32 s28, s28, 0x100
	s_addc_u32 s29, s29, 0
	s_add_u32 s50, s50, 0x100
	s_addc_u32 s51, s51, 0
	s_cmp_gt_u32 s62, 13
